# carry-scan phase: Zhy tile transposes dealt 3 per wave to waves 4-7 and 1 per wave to the carry-scan waves 0-3
# speedup vs baseline: 1.0090x; 1.0008x over previous
.Lgs_census_done:
	v_min_u32_e32 v18, 1, v1
	v_min_u32_e32 v22, 1, v2
	v_add_u32_e32 v18, v18, v22
	v_min_u32_e32 v22, 1, v3
	v_add_u32_e32 v18, v18, v22
	v_min_u32_e32 v22, 1, v4
	v_add_u32_e32 v18, v18, v22
	v_min_u32_e32 v22, 1, v5
	v_add_u32_e32 v18, v18, v22
	v_min_u32_e32 v22, 1, v6
	v_add_u32_e32 v18, v18, v22
	v_min_u32_e32 v22, 1, v7
	v_add_u32_e32 v18, v18, v22
	v_min_u32_e32 v22, 1, v8
	v_add_u32_e32 v18, v18, v22
	v_min_u32_e32 v22, 1, v9
	v_add_u32_e32 v18, v18, v22
	v_min_u32_e32 v22, 1, v10
	v_add_u32_e32 v18, v18, v22
	v_min_u32_e32 v22, 1, v11
	v_add_u32_e32 v18, v18, v22
	v_min_u32_e32 v22, 1, v12
	v_add_u32_e32 v18, v18, v22
	v_min_u32_e32 v22, 1, v13
	v_add_u32_e32 v18, v18, v22
	v_min_u32_e32 v22, 1, v14
	v_add_u32_e32 v18, v18, v22
	v_min_u32_e32 v22, 1, v15
	v_add_u32_e32 v18, v18, v22
	v_min_u32_e32 v22, 1, v16
	v_add_u32_e32 v18, v18, v22
	v_max_u32_e32 v19, 1, v19
	v_max_u32_e32 v18, 1, v18
	v_mov_b32_e32 v22, 0x20ff0
	ds_write_b32 v22, v19
	v_mov_b32_e32 v22, 0x20ff4
	ds_write_b32 v22, v18
	s_waitcnt lgkmcnt(0)
	v_readlane_b32 s98, v248, 1
	v_readlane_b32 s99, v248, 2
	v_mov_b32_e32 v0, 0x20ff0
	ds_read2_b32 v[2:3], v0 offset1:1
	v_mov_b32_e32 v1, 1
	v_mov_b32_e32 v4, s97
	v_lshlrev_b32_e32 v4, 8, v4
	s_add_u32 s98, s98, 0x1000
	s_addc_u32 s99, s99, 0
	s_nop 2
	global_atomic_add v5, v4, v1, s[98:99] offset:1024 sc0
	s_waitcnt vmcnt(0) lgkmcnt(0)
	v_mul_u32_u24_e32 v2, 1, v2
	v_mul_u32_u24_e32 v3, 1, v3
	v_add_u32_e32 v5, 1, v5
	v_cmp_ne_u32_e32 vcc, v5, v2
	v_mov_b32_e32 v6, 0x2400
	s_cbranch_vccnz .Lxb0_poll
	buffer_wbl2 sc1
	s_waitcnt vmcnt(0)
	global_atomic_add v6, v1, s[98:99]


.LBB0_172:
	s_waitcnt vmcnt(0)
	s_barrier
	s_mov_b64 s[0:1], exec
	v_readlane_b32 s2, v248, 3
	v_readlane_b32 s3, v248, 4
	s_and_b64 s[2:3], s[0:1], s[2:3]
	s_mov_b64 exec, s[2:3]
	s_cbranch_execz .LBB0_224
	v_readlane_b32 s98, v248, 1
	v_readlane_b32 s99, v248, 2
	v_mov_b32_e32 v0, 0x20ff0
	ds_read2_b32 v[2:3], v0 offset1:1
	v_mov_b32_e32 v1, 1
	v_mov_b32_e32 v4, s97
	v_lshlrev_b32_e32 v4, 8, v4
	s_add_u32 s98, s98, 0x1000
	s_addc_u32 s99, s99, 0
	s_nop 2
	global_atomic_add v5, v4, v1, s[98:99] offset:1024 sc0
	s_waitcnt vmcnt(0) lgkmcnt(0)
	v_mul_u32_u24_e32 v2, 2, v2
	v_mul_u32_u24_e32 v3, 2, v3
	v_add_u32_e32 v5, 1, v5
	v_cmp_ne_u32_e32 vcc, v5, v2
	v_mov_b32_e32 v6, 0x2400
	s_cbranch_vccnz .Lxb1_poll
	buffer_wbl2 sc1
	s_waitcnt vmcnt(0)
	global_atomic_add v6, v1, s[98:99]


.LBB0_379:
	s_waitcnt vmcnt(0)
	s_waitcnt vmcnt(0)
	s_barrier
	s_mov_b64 s[0:1], exec
	v_readlane_b32 s2, v248, 3
	v_readlane_b32 s3, v248, 4
	s_and_b64 s[2:3], s[0:1], s[2:3]
	s_mov_b64 exec, s[2:3]
	s_cbranch_execz .LBB0_431
	v_readlane_b32 s98, v248, 1
	v_readlane_b32 s99, v248, 2
	v_mov_b32_e32 v0, 0x20ff0
	ds_read2_b32 v[2:3], v0 offset1:1
	v_mov_b32_e32 v1, 1
	v_mov_b32_e32 v4, s97
	v_lshlrev_b32_e32 v4, 8, v4
	s_add_u32 s98, s98, 0x1000
	s_addc_u32 s99, s99, 0
	s_nop 2
	global_atomic_add v5, v4, v1, s[98:99] offset:1024 sc0
	s_waitcnt vmcnt(0) lgkmcnt(0)
	v_mul_u32_u24_e32 v2, 3, v2
	v_mul_u32_u24_e32 v3, 3, v3
	v_add_u32_e32 v5, 1, v5
	v_cmp_ne_u32_e32 vcc, v5, v2
	v_mov_b32_e32 v6, 0x2400
	s_cbranch_vccnz .Lxb2_poll
	buffer_wbl2 sc1
	s_waitcnt vmcnt(0)
	global_atomic_add v6, v1, s[98:99]


.Llt_p3_skip:
	s_waitcnt vmcnt(0)
	s_barrier
	s_mov_b64 s[0:1], exec
	v_readlane_b32 s2, v248, 3
	v_readlane_b32 s3, v248, 4
	s_and_b64 s[2:3], s[0:1], s[2:3]
	s_mov_b64 exec, s[2:3]
	s_cbranch_execz .LBB0_544
	v_readlane_b32 s98, v248, 1
	v_readlane_b32 s99, v248, 2
	v_mov_b32_e32 v0, 0x20ff0
	ds_read2_b32 v[2:3], v0 offset1:1
	v_mov_b32_e32 v1, 1
	v_mov_b32_e32 v4, s97
	v_lshlrev_b32_e32 v4, 8, v4
	s_add_u32 s98, s98, 0x1000
	s_addc_u32 s99, s99, 0
	s_nop 2
	global_atomic_add v5, v4, v1, s[98:99] offset:1024 sc0
	s_waitcnt vmcnt(0) lgkmcnt(0)
	v_mul_u32_u24_e32 v2, 4, v2
	v_mul_u32_u24_e32 v3, 4, v3
	v_add_u32_e32 v5, 1, v5
	v_cmp_ne_u32_e32 vcc, v5, v2
	v_mov_b32_e32 v6, 0x2400
	s_cbranch_vccnz .Lxb3_poll
	buffer_wbl2 sc1
	s_waitcnt vmcnt(0)
	global_atomic_add v6, v1, s[98:99]


.LBB0_551:
	s_or_b64 exec, exec, s[0:1]
	v_mov_b32_e32 v0, v193
	s_nop 0
	v_readfirstlane_b32 s5, v0
	s_ashr_i32 s4, s5, 6
	s_lshl_b32 s2, s6, 4
	s_add_i32 s98, s4, 12
	s_add_i32 s98, s98, s2
	s_add_i32 s99, s98, 1
	s_add_i32 s3, s4, -4
	s_mul_i32 s3, s3, 3
	s_add_i32 s2, s2, s3
	s_add_i32 s3, s2, 3
	s_cmp_gt_i32 s4, 3
	s_cselect_b32 s2, s2, s98
	s_cselect_b32 s98, s3, s99
	s_cmpk_lt_i32 s2, 0x1000
	s_cbranch_scc1 .LBB0_553
	s_mov_b32 s3, 1
	s_cbranch_execz .LBB0_554
	s_branch .LBB0_556
.LBB0_553:
.LBB0_554:
	v_and_b32_e32 v5, 7, v0
	s_mul_i32 s0, s4, 0x2400
	v_bfe_u32 v4, v0, 3, 3
	s_add_i32 s0, s0, 0
	v_lshlrev_b32_e32 v2, 4, v5
	v_mov_b32_e32 v3, 0
	v_lshl_add_u64 v[14:15], s[18:19], 0, v[2:3]
	v_lshlrev_b32_e32 v6, 1, v4
	v_add_u32_e32 v16, s0, v2
	v_lshl_add_u64 v[0:1], s[90:91], 0, v[2:3]
	s_bfe_u32 s5, s5, 0x30006
	v_mul_u32_u24_e32 v2, 0x480, v5
	s_mov_b32 s1, 0
	v_add3_u32 v5, s0, v6, v2
	s_mov_b32 s0, 0
	v_lshl_add_u64 v[0:1], v[0:1], 0, s[0:1]
	s_mov_b64 s[0:1], 0x1b8f0000
	v_or_b32_e32 v6, 8, v4
	v_lshlrev_b32_e32 v2, 16, v4
	v_mul_u32_u24_e32 v13, 0x90, v4
	v_lshl_add_u64 v[0:1], v[0:1], 0, s[0:1]
	v_mul_u32_u24_e32 v17, 0x90, v6
	s_nop 0
	s_lshl_b32 s0, s6, 6
	s_lshl_b32 s1, s4, 3
	s_mov_b32 s3, 1
	v_or_b32_e32 v7, 16, v4
	v_or_b32_e32 v8, 24, v4
	v_or_b32_e32 v9, 32, v4
	v_or_b32_e32 v10, 40, v4
	v_or_b32_e32 v11, 48, v4
	v_or_b32_e32 v12, 56, v4
	v_lshl_add_u64 v[2:3], v[14:15], 0, v[2:3]
	s_lshl_b32 s4, s2, 3
	s_mov_b32 s5, 8
	s_mov_b32 s7, 0x80000
	s_mov_b32 s8, 0x100000
	s_mov_b32 s9, 0x180000
	s_mov_b32 s10, 0x200000
	s_mov_b32 s11, 0x280000
	s_mov_b32 s12, 0x300000
	s_mov_b32 s13, 0x380000
	v_add_u32_e32 v13, v16, v13
	v_add_u32_e32 v14, v16, v17
.LBB0_555:
	s_and_b32 s0, s4, 0xffffffc0
	v_or_b32_e32 v16, s4, v12
	s_ashr_i32 s1, s0, 31
	s_and_b32 s99, s4, 56
	s_lshl_b32 s100, s99, 18
	s_add_i32 s100, s100, s0
	s_mov_b32 s101, 0
	s_lshl_b32 s99, s99, 4
	v_add_co_u32_e32 v64, vcc, s99, v0
	v_addc_co_u32_e32 v65, vcc, 0, v1, vcc
	v_ashrrev_i32_e32 v17, 31, v16
	s_waitcnt vmcnt(0) lgkmcnt(0)
	v_lshl_add_u64 v[44:45], s[100:101], 1, v[2:3]
	v_lshlrev_b64 v[34:35], 10, v[16:17]
	global_load_dwordx4 v[16:19], v[44:45], off
	v_or_b32_e32 v20, s0, v4
	v_or_b32_e32 v22, s0, v6
	v_ashrrev_i32_e32 v21, 31, v20
	v_add_co_u32_e32 v36, vcc, s7, v44
	v_ashrrev_i32_e32 v23, 31, v22
	v_lshlrev_b64 v[20:21], 10, v[20:21]
	v_addc_co_u32_e32 v37, vcc, 0, v45, vcc
	v_lshlrev_b64 v[48:49], 10, v[22:23]
	v_lshl_add_u64 v[62:63], v[64:65], 0, v[20:21]
	global_load_dwordx4 v[20:23], v[36:37], off
	v_or_b32_e32 v24, s0, v7
	v_ashrrev_i32_e32 v25, 31, v24
	v_or_b32_e32 v26, s0, v8
	v_lshlrev_b64 v[50:51], 10, v[24:25]
	v_add_co_u32_e32 v24, vcc, s8, v44
	v_ashrrev_i32_e32 v27, 31, v26
	s_nop 0
	v_addc_co_u32_e32 v25, vcc, 0, v45, vcc
	v_lshlrev_b64 v[52:53], 10, v[26:27]
	global_load_dwordx4 v[24:27], v[24:25], off
	v_or_b32_e32 v28, s0, v9
	v_ashrrev_i32_e32 v29, 31, v28
	v_or_b32_e32 v30, s0, v10
	v_lshlrev_b64 v[54:55], 10, v[28:29]
	v_add_co_u32_e32 v28, vcc, s9, v44
	v_ashrrev_i32_e32 v31, 31, v30
	s_nop 0
	v_addc_co_u32_e32 v29, vcc, 0, v45, vcc
	v_lshlrev_b64 v[56:57], 10, v[30:31]
	global_load_dwordx4 v[28:31], v[28:29], off
	v_or_b32_e32 v32, s0, v11
	v_ashrrev_i32_e32 v33, 31, v32
	v_lshlrev_b64 v[58:59], 10, v[32:33]
	v_add_co_u32_e32 v32, vcc, s10, v44
	v_lshl_add_u64 v[60:61], v[64:65], 0, v[34:35]
	s_nop 0
	v_addc_co_u32_e32 v33, vcc, 0, v45, vcc
	global_load_dwordx4 v[32:35], v[32:33], off
	v_add_co_u32_e32 v36, vcc, s11, v44
	v_lshl_add_u64 v[48:49], v[64:65], 0, v[48:49]
	s_nop 0
	v_addc_co_u32_e32 v37, vcc, 0, v45, vcc
	global_load_dwordx4 v[36:39], v[36:37], off
	v_add_co_u32_e32 v40, vcc, s12, v44
	v_lshl_add_u64 v[50:51], v[64:65], 0, v[50:51]
	s_nop 0
	v_addc_co_u32_e32 v41, vcc, 0, v45, vcc
	global_load_dwordx4 v[40:43], v[40:41], off
	v_add_co_u32_e32 v44, vcc, s13, v44
	v_lshl_add_u64 v[52:53], v[64:65], 0, v[52:53]
	s_nop 0
	v_addc_co_u32_e32 v45, vcc, 0, v45, vcc
	global_load_dwordx4 v[44:47], v[44:45], off
	v_lshl_add_u64 v[54:55], v[64:65], 0, v[54:55]
	v_lshl_add_u64 v[56:57], v[64:65], 0, v[56:57]
	v_lshl_add_u64 v[58:59], v[64:65], 0, v[58:59]
	s_add_i32 s2, s2, s3
	s_add_i32 s4, s4, s5
	s_cmp_lt_i32 s2, s98
	s_waitcnt vmcnt(7)
	ds_write_b16 v5, v16
	ds_write_b16_d16_hi v5, v16 offset:144
	ds_write_b16 v5, v17 offset:288
	ds_write_b16_d16_hi v5, v17 offset:432
	ds_write_b16 v5, v18 offset:576
	ds_write_b16_d16_hi v5, v18 offset:720
	ds_write_b16 v5, v19 offset:864
	ds_write_b16_d16_hi v5, v19 offset:1008
	s_waitcnt vmcnt(6)
	ds_write_b16 v5, v20 offset:16
	ds_write_b16_d16_hi v5, v20 offset:160
	ds_write_b16 v5, v21 offset:304
	ds_write_b16_d16_hi v5, v21 offset:448
	ds_write_b16 v5, v22 offset:592
	ds_write_b16_d16_hi v5, v22 offset:736
	ds_write_b16 v5, v23 offset:880
	ds_write_b16_d16_hi v5, v23 offset:1024
	s_waitcnt vmcnt(5)
	ds_write_b16 v5, v24 offset:32
	ds_write_b16_d16_hi v5, v24 offset:176
	ds_write_b16 v5, v25 offset:320
	ds_write_b16_d16_hi v5, v25 offset:464
	ds_write_b16 v5, v26 offset:608
	ds_write_b16_d16_hi v5, v26 offset:752
	ds_write_b16 v5, v27 offset:896
	ds_write_b16_d16_hi v5, v27 offset:1040
	s_waitcnt vmcnt(4)
	ds_write_b16 v5, v28 offset:48
	ds_write_b16_d16_hi v5, v28 offset:192
	ds_write_b16 v5, v29 offset:336
	ds_write_b16_d16_hi v5, v29 offset:480
	ds_write_b16 v5, v30 offset:624
	ds_write_b16_d16_hi v5, v30 offset:768
	ds_write_b16 v5, v31 offset:912
	ds_write_b16_d16_hi v5, v31 offset:1056
	s_waitcnt vmcnt(3)
	ds_write_b16 v5, v32 offset:64
	ds_write_b16_d16_hi v5, v32 offset:208
	ds_write_b16 v5, v33 offset:352
	ds_write_b16_d16_hi v5, v33 offset:496
	ds_write_b16 v5, v34 offset:640
	ds_write_b16_d16_hi v5, v34 offset:784
	ds_write_b16 v5, v35 offset:928
	ds_write_b16_d16_hi v5, v35 offset:1072
	s_waitcnt vmcnt(2)
	ds_write_b16 v5, v36 offset:80
	ds_write_b16_d16_hi v5, v36 offset:224
	ds_write_b16 v5, v37 offset:368
	ds_write_b16_d16_hi v5, v37 offset:512
	ds_write_b16 v5, v38 offset:656
	ds_write_b16_d16_hi v5, v38 offset:800
	ds_write_b16 v5, v39 offset:944
	ds_write_b16_d16_hi v5, v39 offset:1088
	s_waitcnt vmcnt(1)
	ds_write_b16 v5, v40 offset:96
	ds_write_b16_d16_hi v5, v40 offset:240
	ds_write_b16 v5, v41 offset:384
	ds_write_b16_d16_hi v5, v41 offset:528
	ds_write_b16 v5, v42 offset:672
	ds_write_b16_d16_hi v5, v42 offset:816
	ds_write_b16 v5, v43 offset:960
	ds_write_b16_d16_hi v5, v43 offset:1104
	s_waitcnt vmcnt(0)
	ds_write_b16 v5, v44 offset:112
	ds_write_b16_d16_hi v5, v44 offset:256
	ds_write_b16 v5, v45 offset:400
	ds_write_b16_d16_hi v5, v45 offset:544
	ds_write_b16 v5, v46 offset:688
	ds_write_b16_d16_hi v5, v46 offset:832
	ds_write_b16 v5, v47 offset:976
	ds_write_b16_d16_hi v5, v47 offset:1120
	s_waitcnt lgkmcnt(0)
	ds_read_b128 v[16:19], v13
	ds_read_b128 v[20:23], v14
	ds_read_b128 v[24:27], v14 offset:1152
	ds_read_b128 v[28:31], v14 offset:2304
	ds_read_b128 v[32:35], v14 offset:3456
	ds_read_b128 v[36:39], v14 offset:4608
	ds_read_b128 v[40:43], v14 offset:5760
	ds_read_b128 v[44:47], v14 offset:6912
	s_waitcnt lgkmcnt(7)
	global_store_dwordx4 v[62:63], v[16:19], off
	s_waitcnt lgkmcnt(6)
	global_store_dwordx4 v[48:49], v[20:23], off
	s_waitcnt lgkmcnt(5)
	global_store_dwordx4 v[50:51], v[24:27], off
	s_waitcnt lgkmcnt(4)
	global_store_dwordx4 v[52:53], v[28:31], off
	s_waitcnt lgkmcnt(3)
	global_store_dwordx4 v[54:55], v[32:35], off
	s_waitcnt lgkmcnt(2)
	global_store_dwordx4 v[56:57], v[36:39], off
	s_waitcnt lgkmcnt(1)
	global_store_dwordx4 v[58:59], v[40:43], off
	s_waitcnt lgkmcnt(0)
	global_store_dwordx4 v[60:61], v[44:47], off
	s_waitcnt lgkmcnt(0)
	s_cbranch_scc1 .LBB0_555

.LBB0_589:
	s_cmp_eq_u32 s101, 1
	s_cbranch_scc1 .Llt_p3_return
	s_waitcnt vmcnt(0)
	s_barrier
	s_and_saveexec_b64 s[0:1], s[80:81]
	s_cbranch_execz .LBB0_641
	v_readlane_b32 s98, v248, 1
	v_readlane_b32 s99, v248, 2
	v_mov_b32_e32 v0, 0x20ff0
	ds_read2_b32 v[2:3], v0 offset1:1
	v_mov_b32_e32 v1, 1
	v_mov_b32_e32 v4, s97
	v_lshlrev_b32_e32 v4, 8, v4
	s_add_u32 s98, s98, 0x1000
	s_addc_u32 s99, s99, 0
	s_nop 2
	global_atomic_add v5, v4, v1, s[98:99] offset:1024 sc0
	s_waitcnt vmcnt(0) lgkmcnt(0)
	v_mul_u32_u24_e32 v2, 5, v2
	v_mul_u32_u24_e32 v3, 5, v3
	v_add_u32_e32 v5, 1, v5
	v_cmp_ne_u32_e32 vcc, v5, v2
	v_mov_b32_e32 v6, 0x2400
	s_cbranch_vccnz .Lxb4_poll
	buffer_wbl2 sc1
	s_waitcnt vmcnt(0)
	global_atomic_add v6, v1, s[98:99]


.LBB0_657:
	s_mov_b32 s6, s101
	s_waitcnt vmcnt(0)
	s_waitcnt vmcnt(0)
	s_barrier
	s_and_saveexec_b64 s[8:9], s[80:81]
	s_cbranch_execz .LBB0_709
	v_readlane_b32 s98, v248, 1
	v_readlane_b32 s99, v248, 2
	v_mov_b32_e32 v0, 0x20ff0
	ds_read2_b32 v[2:3], v0 offset1:1
	v_mov_b32_e32 v1, 1
	v_mov_b32_e32 v4, s97
	v_lshlrev_b32_e32 v4, 8, v4
	s_add_u32 s98, s98, 0x1000
	s_addc_u32 s99, s99, 0
	s_nop 2
	global_atomic_add v5, v4, v1, s[98:99] offset:1024 sc0
	s_waitcnt vmcnt(0) lgkmcnt(0)
	v_mul_u32_u24_e32 v2, 6, v2
	v_mul_u32_u24_e32 v3, 6, v3
	v_add_u32_e32 v5, 1, v5
	v_cmp_ne_u32_e32 vcc, v5, v2
	v_mov_b32_e32 v6, 0x2400
	s_cbranch_vccnz .Lxb5_poll
	buffer_wbl2 sc1
	s_waitcnt vmcnt(0)
	global_atomic_add v6, v1, s[98:99]


.LBB0_733:
	s_waitcnt vmcnt(0)
	s_barrier
	s_and_saveexec_b64 s[0:1], s[80:81]
	s_cbranch_execz .LBB0_785
	v_readlane_b32 s98, v248, 1
	v_readlane_b32 s99, v248, 2
	v_mov_b32_e32 v0, 0x20ff0
	ds_read2_b32 v[2:3], v0 offset1:1
	v_mov_b32_e32 v1, 1
	v_mov_b32_e32 v4, s97
	v_lshlrev_b32_e32 v4, 8, v4
	s_add_u32 s98, s98, 0x1000
	s_addc_u32 s99, s99, 0
	s_nop 2
	global_atomic_add v5, v4, v1, s[98:99] offset:1024 sc0
	s_waitcnt vmcnt(0) lgkmcnt(0)
	v_mul_u32_u24_e32 v2, 7, v2
	v_mul_u32_u24_e32 v3, 7, v3
	v_add_u32_e32 v5, 1, v5
	v_cmp_ne_u32_e32 vcc, v5, v2
	v_mov_b32_e32 v6, 0x2400
	s_cbranch_vccnz .Lxb6_poll
	buffer_wbl2 sc1
	s_waitcnt vmcnt(0)
	global_atomic_add v6, v1, s[98:99]


.LBB0_909:
	s_waitcnt vmcnt(0)
	s_barrier
	s_and_saveexec_b64 s[0:1], s[80:81]
	s_cbranch_execz .LBB0_961
	v_readlane_b32 s98, v248, 1
	v_readlane_b32 s99, v248, 2
	v_mov_b32_e32 v0, 0x20ff0
	ds_read2_b32 v[2:3], v0 offset1:1
	v_mov_b32_e32 v1, 1
	v_mov_b32_e32 v4, s97
	v_lshlrev_b32_e32 v4, 8, v4
	s_add_u32 s98, s98, 0x1000
	s_addc_u32 s99, s99, 0
	s_nop 2
	global_atomic_add v5, v4, v1, s[98:99] offset:1024 sc0
	s_waitcnt vmcnt(0) lgkmcnt(0)
	v_mul_u32_u24_e32 v2, 8, v2
	v_mul_u32_u24_e32 v3, 8, v3
	v_add_u32_e32 v5, 1, v5
	v_cmp_ne_u32_e32 vcc, v5, v2
	v_mov_b32_e32 v6, 0x2400
	s_cbranch_vccnz .Lxb7_poll
	buffer_wbl2 sc1
	s_waitcnt vmcnt(0)
	global_atomic_add v6, v1, s[98:99]


.LBB0_985:
	s_waitcnt vmcnt(0)
	s_barrier
	s_and_saveexec_b64 s[0:1], s[80:81]
	s_cbranch_execz .LBB0_1037
	v_readlane_b32 s98, v248, 1
	v_readlane_b32 s99, v248, 2
	v_mov_b32_e32 v0, 0x20ff0
	ds_read2_b32 v[2:3], v0 offset1:1
	v_mov_b32_e32 v1, 1
	v_mov_b32_e32 v4, s97
	v_lshlrev_b32_e32 v4, 8, v4
	s_add_u32 s98, s98, 0x1000
	s_addc_u32 s99, s99, 0
	s_nop 2
	global_atomic_add v5, v4, v1, s[98:99] offset:1024 sc0
	s_waitcnt vmcnt(0) lgkmcnt(0)
	v_mul_u32_u24_e32 v2, 9, v2
	v_mul_u32_u24_e32 v3, 9, v3
	v_add_u32_e32 v5, 1, v5
	v_cmp_ne_u32_e32 vcc, v5, v2
	v_mov_b32_e32 v6, 0x2400
	s_cbranch_vccnz .Lxb8_poll
	buffer_wbl2 sc1
	s_waitcnt vmcnt(0)
	global_atomic_add v6, v1, s[98:99]


.LBB0_1040:
	s_or_b64 exec, exec, s[24:25]
	s_waitcnt vmcnt(0)
	s_barrier
	s_and_saveexec_b64 s[0:1], s[80:81]
	s_cbranch_execz .LBB0_1092
	v_readlane_b32 s98, v248, 1
	v_readlane_b32 s99, v248, 2
	v_mov_b32_e32 v0, 0x20ff0
	ds_read2_b32 v[2:3], v0 offset1:1
	v_mov_b32_e32 v1, 1
	v_mov_b32_e32 v4, s97
	v_lshlrev_b32_e32 v4, 8, v4
	s_add_u32 s98, s98, 0x1000
	s_addc_u32 s99, s99, 0
	s_nop 2
	global_atomic_add v5, v4, v1, s[98:99] offset:1024 sc0
	s_waitcnt vmcnt(0) lgkmcnt(0)
	v_mul_u32_u24_e32 v2, 10, v2
	v_mul_u32_u24_e32 v3, 10, v3
	v_add_u32_e32 v5, 1, v5
	v_cmp_ne_u32_e32 vcc, v5, v2
	v_mov_b32_e32 v6, 0x2400
	s_cbranch_vccnz .Lxb9_poll
	buffer_wbl2 sc1
	s_waitcnt vmcnt(0)
	global_atomic_add v6, v1, s[98:99]


.LBB0_1108:
	s_waitcnt vmcnt(0)
	s_waitcnt vmcnt(0)
	s_barrier
	s_and_saveexec_b64 s[0:1], s[80:81]
	s_cbranch_execz .LBB0_1160
	v_readlane_b32 s98, v248, 1
	v_readlane_b32 s99, v248, 2
	v_mov_b32_e32 v0, 0x20ff0
	ds_read2_b32 v[2:3], v0 offset1:1
	v_mov_b32_e32 v1, 1
	v_mov_b32_e32 v4, s97
	v_lshlrev_b32_e32 v4, 8, v4
	s_add_u32 s98, s98, 0x1000
	s_addc_u32 s99, s99, 0
	s_nop 2
	global_atomic_add v5, v4, v1, s[98:99] offset:1024 sc0
	s_waitcnt vmcnt(0) lgkmcnt(0)
	v_mul_u32_u24_e32 v2, 11, v2
	v_mul_u32_u24_e32 v3, 11, v3
	v_add_u32_e32 v5, 1, v5
	v_cmp_ne_u32_e32 vcc, v5, v2
	v_mov_b32_e32 v6, 0x2400
	s_cbranch_vccnz .Lxb10_poll
	buffer_wbl2 sc1
	s_waitcnt vmcnt(0)
	global_atomic_add v6, v1, s[98:99]


.LBB0_1184:
	s_waitcnt vmcnt(0)
	s_barrier
	s_and_saveexec_b64 s[0:1], s[80:81]
	s_cbranch_execz .LBB0_1236
	v_readlane_b32 s98, v248, 1
	v_readlane_b32 s99, v248, 2
	v_mov_b32_e32 v0, 0x20ff0
	ds_read2_b32 v[2:3], v0 offset1:1
	v_mov_b32_e32 v1, 1
	v_mov_b32_e32 v4, s97
	v_lshlrev_b32_e32 v4, 8, v4
	s_add_u32 s98, s98, 0x1000
	s_addc_u32 s99, s99, 0
	s_nop 2
	global_atomic_add v5, v4, v1, s[98:99] offset:1024 sc0
	s_waitcnt vmcnt(0) lgkmcnt(0)
	v_mul_u32_u24_e32 v2, 12, v2
	v_mul_u32_u24_e32 v3, 12, v3
	v_add_u32_e32 v5, 1, v5
	v_cmp_ne_u32_e32 vcc, v5, v2
	v_mov_b32_e32 v6, 0x2400
	s_cbranch_vccnz .Lxb11_poll
	buffer_wbl2 sc1
	s_waitcnt vmcnt(0)
	global_atomic_add v6, v1, s[98:99]

